# conv mixer items: scalar f32 mul/fma pairs instead of packed VOP3P ops
# baseline (speedup 1.0000x reference)
.Lcv_lastdone:
	s_mov_b32 s38, 0
	s_mul_i32 s7, s21, 0
	s_add_u32 s7, s7, s0
	s_min_u32 s7, s7, s8
	s_lshl_b32 s12, s7, 3
	s_add_u32 s12, s12, s6
	s_cmpk_lt_u32 s12, 0x1000
	s_movk_i32 s9, 0x3ff
	s_cselect_b32 s9, 0xff, s9
	s_and_b32 s10, s12, s9
	s_mul_i32 s11, s12, 0x3400
	s_cmp_eq_u32 s10, 0
	s_cselect_b32 s39, 0, 0x3400
	s_cselect_b32 s7, 1, 0
	s_or_b32 s38, s38, s7
	s_sub_u32 s39, s11, s39
	s_cmp_eq_u32 s10, s9
	s_cselect_b32 s10, 0, 0x3400
	s_cselect_b32 s7, 2, 0
	s_or_b32 s38, s38, s7
	s_add_u32 s10, s11, s10
	v_add_u32_e32 v247, s11, v244
	global_load_dwordx4 v[72:75], v247, s[4:5]
	global_load_dwordx4 v[76:79], v247, s[4:5] offset:1024
	global_load_dwordx4 v[80:83], v247, s[4:5] offset:2048
	v_add_u32_e32 v247, s39, v244
	global_load_dwordx4 v[84:87], v247, s[4:5] offset:1024
	global_load_dwordx4 v[88:91], v247, s[4:5] offset:2048
	v_add_u32_e32 v247, s10, v244
	global_load_dwordx4 v[92:95], v247, s[4:5] offset:1024
	global_load_dwordx4 v[96:99], v247, s[4:5] offset:2048
	s_mul_i32 s7, s21, 1
	s_add_u32 s7, s7, s0
	s_min_u32 s7, s7, s8
	s_lshl_b32 s13, s7, 3
	s_add_u32 s13, s13, s6
	s_cmpk_lt_u32 s13, 0x1000
	s_movk_i32 s9, 0x3ff
	s_cselect_b32 s9, 0xff, s9
	s_and_b32 s10, s13, s9
	s_mul_i32 s11, s13, 0x3400
	s_cmp_eq_u32 s10, 0
	s_cselect_b32 s39, 0, 0x3400
	s_cselect_b32 s7, 4, 0
	s_or_b32 s38, s38, s7
	s_sub_u32 s39, s11, s39
	s_cmp_eq_u32 s10, s9
	s_cselect_b32 s10, 0, 0x3400
	s_cselect_b32 s7, 8, 0
	s_or_b32 s38, s38, s7
	s_add_u32 s10, s11, s10
	v_add_u32_e32 v247, s11, v244
	global_load_dwordx4 v[100:103], v247, s[4:5]
	global_load_dwordx4 v[104:107], v247, s[4:5] offset:1024
	global_load_dwordx4 v[108:111], v247, s[4:5] offset:2048
	v_add_u32_e32 v247, s39, v244
	global_load_dwordx4 v[112:115], v247, s[4:5] offset:1024
	global_load_dwordx4 v[116:119], v247, s[4:5] offset:2048
	v_add_u32_e32 v247, s10, v244
	global_load_dwordx4 v[120:123], v247, s[4:5] offset:1024
	global_load_dwordx4 v[124:127], v247, s[4:5] offset:2048
	s_mul_i32 s7, s21, 2
	s_add_u32 s7, s7, s0
	s_min_u32 s7, s7, s8
	s_lshl_b32 s14, s7, 3
	s_add_u32 s14, s14, s6
	s_cmpk_lt_u32 s14, 0x1000
	s_movk_i32 s9, 0x3ff
	s_cselect_b32 s9, 0xff, s9
	s_and_b32 s10, s14, s9
	s_mul_i32 s11, s14, 0x3400
	s_cmp_eq_u32 s10, 0
	s_cselect_b32 s39, 0, 0x3400
	s_cselect_b32 s7, 16, 0
	s_or_b32 s38, s38, s7
	s_sub_u32 s39, s11, s39
	s_cmp_eq_u32 s10, s9
	s_cselect_b32 s10, 0, 0x3400
	s_cselect_b32 s7, 32, 0
	s_or_b32 s38, s38, s7
	s_add_u32 s10, s11, s10
	v_add_u32_e32 v247, s11, v244
	global_load_dwordx4 v[128:131], v247, s[4:5]
	global_load_dwordx4 v[132:135], v247, s[4:5] offset:1024
	global_load_dwordx4 v[136:139], v247, s[4:5] offset:2048
	v_add_u32_e32 v247, s39, v244
	global_load_dwordx4 v[140:143], v247, s[4:5] offset:1024
	global_load_dwordx4 v[144:147], v247, s[4:5] offset:2048
	v_add_u32_e32 v247, s10, v244
	global_load_dwordx4 v[148:151], v247, s[4:5] offset:1024
	global_load_dwordx4 v[152:155], v247, s[4:5] offset:2048
	s_mul_i32 s7, s21, 3
	s_add_u32 s7, s7, s0
	s_min_u32 s7, s7, s8
	s_lshl_b32 s15, s7, 3
	s_add_u32 s15, s15, s6
	s_cmpk_lt_u32 s15, 0x1000
	s_movk_i32 s9, 0x3ff
	s_cselect_b32 s9, 0xff, s9
	s_and_b32 s10, s15, s9
	s_mul_i32 s11, s15, 0x3400
	s_cmp_eq_u32 s10, 0
	s_cselect_b32 s39, 0, 0x3400
	s_cselect_b32 s7, 64, 0
	s_or_b32 s38, s38, s7
	s_sub_u32 s39, s11, s39
	s_cmp_eq_u32 s10, s9
	s_cselect_b32 s10, 0, 0x3400
	s_cselect_b32 s7, 128, 0
	s_or_b32 s38, s38, s7
	s_add_u32 s10, s11, s10
	v_add_u32_e32 v247, s11, v244
	global_load_dwordx4 v[212:215], v247, s[4:5]
	global_load_dwordx4 v[216:219], v247, s[4:5] offset:1024
	global_load_dwordx4 v[220:223], v247, s[4:5] offset:2048
	v_add_u32_e32 v247, s39, v244
	global_load_dwordx4 v[224:227], v247, s[4:5] offset:1024
	global_load_dwordx4 v[228:231], v247, s[4:5] offset:2048
	v_add_u32_e32 v247, s10, v244
	global_load_dwordx4 v[232:235], v247, s[4:5] offset:1024
	global_load_dwordx4 v[236:239], v247, s[4:5] offset:2048
	s_waitcnt vmcnt(28)
	s_waitcnt vmcnt(21)
	v_lshlrev_b32_e32 v10, 16, v76
	v_and_b32_e32 v11, 0xffff0000, v76
	v_lshlrev_b32_e32 v12, 16, v80
	v_and_b32_e32 v13, 0xffff0000, v80
	v_mul_f32_e32 v14, v10, v12
	v_mul_f32_e32 v15, v11, v13
	s_nop 0
	v_mul_f32_e32 v2, v182, v14
	v_mul_f32_e32 v3, v183, v15
	v_lshlrev_b32_e32 v10, 16, v77
	v_and_b32_e32 v11, 0xffff0000, v77
	v_lshlrev_b32_e32 v12, 16, v81
	v_and_b32_e32 v13, 0xffff0000, v81
	v_mul_f32_e32 v14, v10, v12
	v_mul_f32_e32 v15, v11, v13
	s_nop 0
	v_mul_f32_e32 v4, v184, v14
	v_mul_f32_e32 v5, v185, v15
	v_lshlrev_b32_e32 v10, 16, v78
	v_and_b32_e32 v11, 0xffff0000, v78
	v_lshlrev_b32_e32 v12, 16, v82
	v_and_b32_e32 v13, 0xffff0000, v82
	v_mul_f32_e32 v14, v10, v12
	v_mul_f32_e32 v15, v11, v13
	s_nop 0
	v_mul_f32_e32 v6, v186, v14
	v_mul_f32_e32 v7, v187, v15
	v_lshlrev_b32_e32 v10, 16, v79
	v_and_b32_e32 v11, 0xffff0000, v79
	v_lshlrev_b32_e32 v12, 16, v83
	v_and_b32_e32 v13, 0xffff0000, v83
	v_mul_f32_e32 v14, v10, v12
	v_mul_f32_e32 v15, v11, v13
	s_nop 0
	v_mul_f32_e32 v8, v188, v14
	v_mul_f32_e32 v9, v189, v15
	s_bitcmp1_b32 s38, 0
	s_cbranch_scc1 .Lcv_np0
	v_lshlrev_b32_e32 v10, 16, v84
	v_and_b32_e32 v11, 0xffff0000, v84
	v_lshlrev_b32_e32 v12, 16, v88
	v_and_b32_e32 v13, 0xffff0000, v88
	v_mul_f32_e32 v14, v10, v12
	v_mul_f32_e32 v15, v11, v13
	s_nop 0
	v_fma_f32 v2, v174, v14, v2
	v_fma_f32 v3, v175, v15, v3
	v_lshlrev_b32_e32 v10, 16, v85
	v_and_b32_e32 v11, 0xffff0000, v85
	v_lshlrev_b32_e32 v12, 16, v89
	v_and_b32_e32 v13, 0xffff0000, v89
	v_mul_f32_e32 v14, v10, v12
	v_mul_f32_e32 v15, v11, v13
	s_nop 0
	v_fma_f32 v4, v176, v14, v4
	v_fma_f32 v5, v177, v15, v5
	v_lshlrev_b32_e32 v10, 16, v86
	v_and_b32_e32 v11, 0xffff0000, v86
	v_lshlrev_b32_e32 v12, 16, v90
	v_and_b32_e32 v13, 0xffff0000, v90
	v_mul_f32_e32 v14, v10, v12
	v_mul_f32_e32 v15, v11, v13
	s_nop 0
	v_fma_f32 v6, v178, v14, v6
	v_fma_f32 v7, v179, v15, v7
	v_lshlrev_b32_e32 v10, 16, v87
	v_and_b32_e32 v11, 0xffff0000, v87
	v_lshlrev_b32_e32 v12, 16, v91
	v_and_b32_e32 v13, 0xffff0000, v91
	v_mul_f32_e32 v14, v10, v12
	v_mul_f32_e32 v15, v11, v13
	s_nop 0
	v_fma_f32 v8, v180, v14, v8
	v_fma_f32 v9, v181, v15, v9
.Lcv_np0:
	s_bitcmp1_b32 s38, 1
	s_cbranch_scc1 .Lcv_nn0
	v_lshlrev_b32_e32 v10, 16, v92
	v_and_b32_e32 v11, 0xffff0000, v92
	v_lshlrev_b32_e32 v12, 16, v96
	v_and_b32_e32 v13, 0xffff0000, v96
	v_mul_f32_e32 v14, v10, v12
	v_mul_f32_e32 v15, v11, v13
	s_nop 0
	v_fma_f32 v2, v190, v14, v2
	v_fma_f32 v3, v191, v15, v3
	v_lshlrev_b32_e32 v10, 16, v93
	v_and_b32_e32 v11, 0xffff0000, v93
	v_lshlrev_b32_e32 v12, 16, v97
	v_and_b32_e32 v13, 0xffff0000, v97
	v_mul_f32_e32 v14, v10, v12
	v_mul_f32_e32 v15, v11, v13
	s_nop 0
	v_fma_f32 v4, v192, v14, v4
	v_fma_f32 v5, v193, v15, v5
	v_lshlrev_b32_e32 v10, 16, v94
	v_and_b32_e32 v11, 0xffff0000, v94
	v_lshlrev_b32_e32 v12, 16, v98
	v_and_b32_e32 v13, 0xffff0000, v98
	v_mul_f32_e32 v14, v10, v12
	v_mul_f32_e32 v15, v11, v13
	s_nop 0
	v_fma_f32 v6, v240, v14, v6
	v_fma_f32 v7, v241, v15, v7
	v_lshlrev_b32_e32 v10, 16, v95
	v_and_b32_e32 v11, 0xffff0000, v95
	v_lshlrev_b32_e32 v12, 16, v99
	v_and_b32_e32 v13, 0xffff0000, v99
	v_mul_f32_e32 v14, v10, v12
	v_mul_f32_e32 v15, v11, v13
	s_nop 0
	v_fma_f32 v8, v242, v14, v8
	v_fma_f32 v9, v243, v15, v9
.Lcv_nn0:
	v_lshlrev_b32_e32 v10, 16, v72
	v_and_b32_e32 v11, 0xffff0000, v72
	v_mul_f32_e32 v2, v2, v10
	v_mul_f32_e32 v3, v3, v11
	v_lshlrev_b32_e32 v10, 16, v73
	v_and_b32_e32 v11, 0xffff0000, v73
	v_mul_f32_e32 v4, v4, v10
	v_mul_f32_e32 v5, v5, v11
	v_lshlrev_b32_e32 v10, 16, v74
	v_and_b32_e32 v11, 0xffff0000, v74
	v_mul_f32_e32 v6, v6, v10
	v_mul_f32_e32 v7, v7, v11
	v_lshlrev_b32_e32 v10, 16, v75
	v_and_b32_e32 v11, 0xffff0000, v75
	v_mul_f32_e32 v8, v8, v10
	v_mul_f32_e32 v9, v9, v11
	s_nop 0
	v_cvt_pk_bf16_f32 v72, v2, v3
	v_cvt_pk_bf16_f32 v73, v4, v5
	v_cvt_pk_bf16_f32 v74, v6, v7
	v_cvt_pk_bf16_f32 v75, v8, v9
	s_mul_i32 s7, s12, 0xc00
	v_add_u32_e32 v247, s7, v244
	global_store_dwordx4 v247, v[72:75], s[36:37]
	s_waitcnt vmcnt(15)
	v_lshlrev_b32_e32 v10, 16, v104
	v_and_b32_e32 v11, 0xffff0000, v104
	v_lshlrev_b32_e32 v12, 16, v108
	v_and_b32_e32 v13, 0xffff0000, v108
	v_mul_f32_e32 v14, v10, v12
	v_mul_f32_e32 v15, v11, v13
	s_nop 0
	v_mul_f32_e32 v2, v182, v14
	v_mul_f32_e32 v3, v183, v15
	v_lshlrev_b32_e32 v10, 16, v105
	v_and_b32_e32 v11, 0xffff0000, v105
	v_lshlrev_b32_e32 v12, 16, v109
	v_and_b32_e32 v13, 0xffff0000, v109
	v_mul_f32_e32 v14, v10, v12
	v_mul_f32_e32 v15, v11, v13
	s_nop 0
	v_mul_f32_e32 v4, v184, v14
	v_mul_f32_e32 v5, v185, v15
	v_lshlrev_b32_e32 v10, 16, v106
	v_and_b32_e32 v11, 0xffff0000, v106
	v_lshlrev_b32_e32 v12, 16, v110
	v_and_b32_e32 v13, 0xffff0000, v110
	v_mul_f32_e32 v14, v10, v12
	v_mul_f32_e32 v15, v11, v13
	s_nop 0
	v_mul_f32_e32 v6, v186, v14
	v_mul_f32_e32 v7, v187, v15
	v_lshlrev_b32_e32 v10, 16, v107
	v_and_b32_e32 v11, 0xffff0000, v107
	v_lshlrev_b32_e32 v12, 16, v111
	v_and_b32_e32 v13, 0xffff0000, v111
	v_mul_f32_e32 v14, v10, v12
	v_mul_f32_e32 v15, v11, v13
	s_nop 0
	v_mul_f32_e32 v8, v188, v14
	v_mul_f32_e32 v9, v189, v15
	s_bitcmp1_b32 s38, 2
	s_cbranch_scc1 .Lcv_np1
	v_lshlrev_b32_e32 v10, 16, v112
	v_and_b32_e32 v11, 0xffff0000, v112
	v_lshlrev_b32_e32 v12, 16, v116
	v_and_b32_e32 v13, 0xffff0000, v116
	v_mul_f32_e32 v14, v10, v12
	v_mul_f32_e32 v15, v11, v13
	s_nop 0
	v_fma_f32 v2, v174, v14, v2
	v_fma_f32 v3, v175, v15, v3
	v_lshlrev_b32_e32 v10, 16, v113
	v_and_b32_e32 v11, 0xffff0000, v113
	v_lshlrev_b32_e32 v12, 16, v117
	v_and_b32_e32 v13, 0xffff0000, v117
	v_mul_f32_e32 v14, v10, v12
	v_mul_f32_e32 v15, v11, v13
	s_nop 0
	v_fma_f32 v4, v176, v14, v4
	v_fma_f32 v5, v177, v15, v5
	v_lshlrev_b32_e32 v10, 16, v114
	v_and_b32_e32 v11, 0xffff0000, v114
	v_lshlrev_b32_e32 v12, 16, v118
	v_and_b32_e32 v13, 0xffff0000, v118
	v_mul_f32_e32 v14, v10, v12
	v_mul_f32_e32 v15, v11, v13
	s_nop 0
	v_fma_f32 v6, v178, v14, v6
	v_fma_f32 v7, v179, v15, v7
	v_lshlrev_b32_e32 v10, 16, v115
	v_and_b32_e32 v11, 0xffff0000, v115
	v_lshlrev_b32_e32 v12, 16, v119
	v_and_b32_e32 v13, 0xffff0000, v119
	v_mul_f32_e32 v14, v10, v12
	v_mul_f32_e32 v15, v11, v13
	s_nop 0
	v_fma_f32 v8, v180, v14, v8
	v_fma_f32 v9, v181, v15, v9
.Lcv_np1:
	s_bitcmp1_b32 s38, 3
	s_cbranch_scc1 .Lcv_nn1
	v_lshlrev_b32_e32 v10, 16, v120
	v_and_b32_e32 v11, 0xffff0000, v120
	v_lshlrev_b32_e32 v12, 16, v124
	v_and_b32_e32 v13, 0xffff0000, v124
	v_mul_f32_e32 v14, v10, v12
	v_mul_f32_e32 v15, v11, v13
	s_nop 0
	v_fma_f32 v2, v190, v14, v2
	v_fma_f32 v3, v191, v15, v3
	v_lshlrev_b32_e32 v10, 16, v121
	v_and_b32_e32 v11, 0xffff0000, v121
	v_lshlrev_b32_e32 v12, 16, v125
	v_and_b32_e32 v13, 0xffff0000, v125
	v_mul_f32_e32 v14, v10, v12
	v_mul_f32_e32 v15, v11, v13
	s_nop 0
	v_fma_f32 v4, v192, v14, v4
	v_fma_f32 v5, v193, v15, v5
	v_lshlrev_b32_e32 v10, 16, v122
	v_and_b32_e32 v11, 0xffff0000, v122
	v_lshlrev_b32_e32 v12, 16, v126
	v_and_b32_e32 v13, 0xffff0000, v126
	v_mul_f32_e32 v14, v10, v12
	v_mul_f32_e32 v15, v11, v13
	s_nop 0
	v_fma_f32 v6, v240, v14, v6
	v_fma_f32 v7, v241, v15, v7
	v_lshlrev_b32_e32 v10, 16, v123
	v_and_b32_e32 v11, 0xffff0000, v123
	v_lshlrev_b32_e32 v12, 16, v127
	v_and_b32_e32 v13, 0xffff0000, v127
	v_mul_f32_e32 v14, v10, v12
	v_mul_f32_e32 v15, v11, v13
	s_nop 0
	v_fma_f32 v8, v242, v14, v8
	v_fma_f32 v9, v243, v15, v9
.Lcv_nn1:
	v_lshlrev_b32_e32 v10, 16, v100
	v_and_b32_e32 v11, 0xffff0000, v100
	v_mul_f32_e32 v2, v2, v10
	v_mul_f32_e32 v3, v3, v11
	v_lshlrev_b32_e32 v10, 16, v101
	v_and_b32_e32 v11, 0xffff0000, v101
	v_mul_f32_e32 v4, v4, v10
	v_mul_f32_e32 v5, v5, v11
	v_lshlrev_b32_e32 v10, 16, v102
	v_and_b32_e32 v11, 0xffff0000, v102
	v_mul_f32_e32 v6, v6, v10
	v_mul_f32_e32 v7, v7, v11
	v_lshlrev_b32_e32 v10, 16, v103
	v_and_b32_e32 v11, 0xffff0000, v103
	v_mul_f32_e32 v8, v8, v10
	v_mul_f32_e32 v9, v9, v11
	s_nop 0
	v_cvt_pk_bf16_f32 v100, v2, v3
	v_cvt_pk_bf16_f32 v101, v4, v5
	v_cvt_pk_bf16_f32 v102, v6, v7
	v_cvt_pk_bf16_f32 v103, v8, v9
	s_mul_i32 s7, s13, 0xc00
	v_add_u32_e32 v247, s7, v244
	global_store_dwordx4 v247, v[100:103], s[36:37]
	s_waitcnt vmcnt(9)
	v_lshlrev_b32_e32 v10, 16, v132
	v_and_b32_e32 v11, 0xffff0000, v132
	v_lshlrev_b32_e32 v12, 16, v136
	v_and_b32_e32 v13, 0xffff0000, v136
	v_mul_f32_e32 v14, v10, v12
	v_mul_f32_e32 v15, v11, v13
	s_nop 0
	v_mul_f32_e32 v2, v182, v14
	v_mul_f32_e32 v3, v183, v15
	v_lshlrev_b32_e32 v10, 16, v133
	v_and_b32_e32 v11, 0xffff0000, v133
	v_lshlrev_b32_e32 v12, 16, v137
	v_and_b32_e32 v13, 0xffff0000, v137
	v_mul_f32_e32 v14, v10, v12
	v_mul_f32_e32 v15, v11, v13
	s_nop 0
	v_mul_f32_e32 v4, v184, v14
	v_mul_f32_e32 v5, v185, v15
	v_lshlrev_b32_e32 v10, 16, v134
	v_and_b32_e32 v11, 0xffff0000, v134
	v_lshlrev_b32_e32 v12, 16, v138
	v_and_b32_e32 v13, 0xffff0000, v138
	v_mul_f32_e32 v14, v10, v12
	v_mul_f32_e32 v15, v11, v13
	s_nop 0
	v_mul_f32_e32 v6, v186, v14
	v_mul_f32_e32 v7, v187, v15
	v_lshlrev_b32_e32 v10, 16, v135
	v_and_b32_e32 v11, 0xffff0000, v135
	v_lshlrev_b32_e32 v12, 16, v139
	v_and_b32_e32 v13, 0xffff0000, v139
	v_mul_f32_e32 v14, v10, v12
	v_mul_f32_e32 v15, v11, v13
	s_nop 0
	v_mul_f32_e32 v8, v188, v14
	v_mul_f32_e32 v9, v189, v15
	s_bitcmp1_b32 s38, 4
	s_cbranch_scc1 .Lcv_np2
	v_lshlrev_b32_e32 v10, 16, v140
	v_and_b32_e32 v11, 0xffff0000, v140
	v_lshlrev_b32_e32 v12, 16, v144
	v_and_b32_e32 v13, 0xffff0000, v144
	v_mul_f32_e32 v14, v10, v12
	v_mul_f32_e32 v15, v11, v13
	s_nop 0
	v_fma_f32 v2, v174, v14, v2
	v_fma_f32 v3, v175, v15, v3
	v_lshlrev_b32_e32 v10, 16, v141
	v_and_b32_e32 v11, 0xffff0000, v141
	v_lshlrev_b32_e32 v12, 16, v145
	v_and_b32_e32 v13, 0xffff0000, v145
	v_mul_f32_e32 v14, v10, v12
	v_mul_f32_e32 v15, v11, v13
	s_nop 0
	v_fma_f32 v4, v176, v14, v4
	v_fma_f32 v5, v177, v15, v5
	v_lshlrev_b32_e32 v10, 16, v142
	v_and_b32_e32 v11, 0xffff0000, v142
	v_lshlrev_b32_e32 v12, 16, v146
	v_and_b32_e32 v13, 0xffff0000, v146
	v_mul_f32_e32 v14, v10, v12
	v_mul_f32_e32 v15, v11, v13
	s_nop 0
	v_fma_f32 v6, v178, v14, v6
	v_fma_f32 v7, v179, v15, v7
	v_lshlrev_b32_e32 v10, 16, v143
	v_and_b32_e32 v11, 0xffff0000, v143
	v_lshlrev_b32_e32 v12, 16, v147
	v_and_b32_e32 v13, 0xffff0000, v147
	v_mul_f32_e32 v14, v10, v12
	v_mul_f32_e32 v15, v11, v13
	s_nop 0
	v_fma_f32 v8, v180, v14, v8
	v_fma_f32 v9, v181, v15, v9
.Lcv_np2:
	s_bitcmp1_b32 s38, 5
	s_cbranch_scc1 .Lcv_nn2
	v_lshlrev_b32_e32 v10, 16, v148
	v_and_b32_e32 v11, 0xffff0000, v148
	v_lshlrev_b32_e32 v12, 16, v152
	v_and_b32_e32 v13, 0xffff0000, v152
	v_mul_f32_e32 v14, v10, v12
	v_mul_f32_e32 v15, v11, v13
	s_nop 0
	v_fma_f32 v2, v190, v14, v2
	v_fma_f32 v3, v191, v15, v3
	v_lshlrev_b32_e32 v10, 16, v149
	v_and_b32_e32 v11, 0xffff0000, v149
	v_lshlrev_b32_e32 v12, 16, v153
	v_and_b32_e32 v13, 0xffff0000, v153
	v_mul_f32_e32 v14, v10, v12
	v_mul_f32_e32 v15, v11, v13
	s_nop 0
	v_fma_f32 v4, v192, v14, v4
	v_fma_f32 v5, v193, v15, v5
	v_lshlrev_b32_e32 v10, 16, v150
	v_and_b32_e32 v11, 0xffff0000, v150
	v_lshlrev_b32_e32 v12, 16, v154
	v_and_b32_e32 v13, 0xffff0000, v154
	v_mul_f32_e32 v14, v10, v12
	v_mul_f32_e32 v15, v11, v13
	s_nop 0
	v_fma_f32 v6, v240, v14, v6
	v_fma_f32 v7, v241, v15, v7
	v_lshlrev_b32_e32 v10, 16, v151
	v_and_b32_e32 v11, 0xffff0000, v151
	v_lshlrev_b32_e32 v12, 16, v155
	v_and_b32_e32 v13, 0xffff0000, v155
	v_mul_f32_e32 v14, v10, v12
	v_mul_f32_e32 v15, v11, v13
	s_nop 0
	v_fma_f32 v8, v242, v14, v8
	v_fma_f32 v9, v243, v15, v9
.Lcv_nn2:
	v_lshlrev_b32_e32 v10, 16, v128
	v_and_b32_e32 v11, 0xffff0000, v128
	v_mul_f32_e32 v2, v2, v10
	v_mul_f32_e32 v3, v3, v11
	v_lshlrev_b32_e32 v10, 16, v129
	v_and_b32_e32 v11, 0xffff0000, v129
	v_mul_f32_e32 v4, v4, v10
	v_mul_f32_e32 v5, v5, v11
	v_lshlrev_b32_e32 v10, 16, v130
	v_and_b32_e32 v11, 0xffff0000, v130
	v_mul_f32_e32 v6, v6, v10
	v_mul_f32_e32 v7, v7, v11
	v_lshlrev_b32_e32 v10, 16, v131
	v_and_b32_e32 v11, 0xffff0000, v131
	v_mul_f32_e32 v8, v8, v10
	v_mul_f32_e32 v9, v9, v11
	s_nop 0
	v_cvt_pk_bf16_f32 v128, v2, v3
	v_cvt_pk_bf16_f32 v129, v4, v5
	v_cvt_pk_bf16_f32 v130, v6, v7
	v_cvt_pk_bf16_f32 v131, v8, v9
	s_mul_i32 s7, s14, 0xc00
	v_add_u32_e32 v247, s7, v244
	global_store_dwordx4 v247, v[128:131], s[36:37]
	s_waitcnt vmcnt(3)
	v_lshlrev_b32_e32 v10, 16, v216
	v_and_b32_e32 v11, 0xffff0000, v216
	v_lshlrev_b32_e32 v12, 16, v220
	v_and_b32_e32 v13, 0xffff0000, v220
	v_mul_f32_e32 v14, v10, v12
	v_mul_f32_e32 v15, v11, v13
	s_nop 0
	v_mul_f32_e32 v2, v182, v14
	v_mul_f32_e32 v3, v183, v15
	v_lshlrev_b32_e32 v10, 16, v217
	v_and_b32_e32 v11, 0xffff0000, v217
	v_lshlrev_b32_e32 v12, 16, v221
	v_and_b32_e32 v13, 0xffff0000, v221
	v_mul_f32_e32 v14, v10, v12
	v_mul_f32_e32 v15, v11, v13
	s_nop 0
	v_mul_f32_e32 v4, v184, v14
	v_mul_f32_e32 v5, v185, v15
	v_lshlrev_b32_e32 v10, 16, v218
	v_and_b32_e32 v11, 0xffff0000, v218
	v_lshlrev_b32_e32 v12, 16, v222
	v_and_b32_e32 v13, 0xffff0000, v222
	v_mul_f32_e32 v14, v10, v12
	v_mul_f32_e32 v15, v11, v13
	s_nop 0
	v_mul_f32_e32 v6, v186, v14
	v_mul_f32_e32 v7, v187, v15
	v_lshlrev_b32_e32 v10, 16, v219
	v_and_b32_e32 v11, 0xffff0000, v219
	v_lshlrev_b32_e32 v12, 16, v223
	v_and_b32_e32 v13, 0xffff0000, v223
	v_mul_f32_e32 v14, v10, v12
	v_mul_f32_e32 v15, v11, v13
	s_nop 0
	v_mul_f32_e32 v8, v188, v14
	v_mul_f32_e32 v9, v189, v15
	s_bitcmp1_b32 s38, 6
	s_cbranch_scc1 .Lcv_np3
	v_lshlrev_b32_e32 v10, 16, v224
	v_and_b32_e32 v11, 0xffff0000, v224
	v_lshlrev_b32_e32 v12, 16, v228
	v_and_b32_e32 v13, 0xffff0000, v228
	v_mul_f32_e32 v14, v10, v12
	v_mul_f32_e32 v15, v11, v13
	s_nop 0
	v_fma_f32 v2, v174, v14, v2
	v_fma_f32 v3, v175, v15, v3
	v_lshlrev_b32_e32 v10, 16, v225
	v_and_b32_e32 v11, 0xffff0000, v225
	v_lshlrev_b32_e32 v12, 16, v229
	v_and_b32_e32 v13, 0xffff0000, v229
	v_mul_f32_e32 v14, v10, v12
	v_mul_f32_e32 v15, v11, v13
	s_nop 0
	v_fma_f32 v4, v176, v14, v4
	v_fma_f32 v5, v177, v15, v5
	v_lshlrev_b32_e32 v10, 16, v226
	v_and_b32_e32 v11, 0xffff0000, v226
	v_lshlrev_b32_e32 v12, 16, v230
	v_and_b32_e32 v13, 0xffff0000, v230
	v_mul_f32_e32 v14, v10, v12
	v_mul_f32_e32 v15, v11, v13
	s_nop 0
	v_fma_f32 v6, v178, v14, v6
	v_fma_f32 v7, v179, v15, v7
	v_lshlrev_b32_e32 v10, 16, v227
	v_and_b32_e32 v11, 0xffff0000, v227
	v_lshlrev_b32_e32 v12, 16, v231
	v_and_b32_e32 v13, 0xffff0000, v231
	v_mul_f32_e32 v14, v10, v12
	v_mul_f32_e32 v15, v11, v13
	s_nop 0
	v_fma_f32 v8, v180, v14, v8
	v_fma_f32 v9, v181, v15, v9
.Lcv_np3:
	s_bitcmp1_b32 s38, 7
	s_cbranch_scc1 .Lcv_nn3
	v_lshlrev_b32_e32 v10, 16, v232
	v_and_b32_e32 v11, 0xffff0000, v232
	v_lshlrev_b32_e32 v12, 16, v236
	v_and_b32_e32 v13, 0xffff0000, v236
	v_mul_f32_e32 v14, v10, v12
	v_mul_f32_e32 v15, v11, v13
	s_nop 0
	v_fma_f32 v2, v190, v14, v2
	v_fma_f32 v3, v191, v15, v3
	v_lshlrev_b32_e32 v10, 16, v233
	v_and_b32_e32 v11, 0xffff0000, v233
	v_lshlrev_b32_e32 v12, 16, v237
	v_and_b32_e32 v13, 0xffff0000, v237
	v_mul_f32_e32 v14, v10, v12
	v_mul_f32_e32 v15, v11, v13
	s_nop 0
	v_fma_f32 v4, v192, v14, v4
	v_fma_f32 v5, v193, v15, v5
	v_lshlrev_b32_e32 v10, 16, v234
	v_and_b32_e32 v11, 0xffff0000, v234
	v_lshlrev_b32_e32 v12, 16, v238
	v_and_b32_e32 v13, 0xffff0000, v238
	v_mul_f32_e32 v14, v10, v12
	v_mul_f32_e32 v15, v11, v13
	s_nop 0
	v_fma_f32 v6, v240, v14, v6
	v_fma_f32 v7, v241, v15, v7
	v_lshlrev_b32_e32 v10, 16, v235
	v_and_b32_e32 v11, 0xffff0000, v235
	v_lshlrev_b32_e32 v12, 16, v239
	v_and_b32_e32 v13, 0xffff0000, v239
	v_mul_f32_e32 v14, v10, v12
	v_mul_f32_e32 v15, v11, v13
	s_nop 0
	v_fma_f32 v8, v242, v14, v8
	v_fma_f32 v9, v243, v15, v9
.Lcv_nn3:
	v_lshlrev_b32_e32 v10, 16, v212
	v_and_b32_e32 v11, 0xffff0000, v212
	v_mul_f32_e32 v2, v2, v10
	v_mul_f32_e32 v3, v3, v11
	v_lshlrev_b32_e32 v10, 16, v213
	v_and_b32_e32 v11, 0xffff0000, v213
	v_mul_f32_e32 v4, v4, v10
	v_mul_f32_e32 v5, v5, v11
	v_lshlrev_b32_e32 v10, 16, v214
	v_and_b32_e32 v11, 0xffff0000, v214
	v_mul_f32_e32 v6, v6, v10
	v_mul_f32_e32 v7, v7, v11
	v_lshlrev_b32_e32 v10, 16, v215
	v_and_b32_e32 v11, 0xffff0000, v215
	v_mul_f32_e32 v8, v8, v10
	v_mul_f32_e32 v9, v9, v11
	s_nop 0
	v_cvt_pk_bf16_f32 v212, v2, v3
	v_cvt_pk_bf16_f32 v213, v4, v5
	v_cvt_pk_bf16_f32 v214, v6, v7
	v_cvt_pk_bf16_f32 v215, v8, v9
	s_mul_i32 s7, s15, 0xc00
	v_add_u32_e32 v247, s7, v244
	global_store_dwordx4 v247, v[212:215], s[36:37]
